# final RMSNorm loop de-serialised: x-row loads of rows 2/3 issued with rows 0/1 right after the ss loads (row 3 into spare registers, copied back at first use), vmcnt waits re-derived by op identity
# speedup vs baseline: 1.0018x; 1.0018x over previous
.LBB0_15:
	v_ashrrev_i32_e32 v23, 31, v22
	v_lshl_add_u64 v[80:81], v[22:23], 2, s[14:15]
	v_add_co_u32_e32 v28, vcc, s77, v80
	global_load_dwordx4 v[18:21], v[80:81], off
	s_nop 0
	v_addc_co_u32_e32 v29, vcc, 0, v81, vcc
	v_add_co_u32_e32 v32, vcc, s78, v80
	global_load_dwordx4 v[28:31], v[28:29], off
	s_nop 0
	v_addc_co_u32_e32 v33, vcc, 0, v81, vcc
	v_add_co_u32_e32 v36, vcc, s79, v80
	v_lshlrev_b64 v[88:89], 11, v[22:23]
	s_nop 0
	v_addc_co_u32_e32 v37, vcc, 0, v81, vcc
	v_add_co_u32_e32 v40, vcc, s94, v80
	global_load_dwordx4 v[32:35], v[32:33], off
	s_nop 0
	global_load_dwordx4 v[36:39], v[36:37], off
	v_addc_co_u32_e32 v41, vcc, 0, v81, vcc
	v_add_co_u32_e32 v44, vcc, s95, v80
	v_lshl_add_u64 v[96:97], v[24:25], 0, v[88:89]
	s_nop 0
	v_addc_co_u32_e32 v45, vcc, 0, v81, vcc
	v_add_co_u32_e32 v48, vcc, s96, v80
	global_load_dwordx4 v[40:43], v[40:41], off
	s_nop 0
	global_load_dwordx4 v[44:47], v[44:45], off
	v_addc_co_u32_e32 v49, vcc, 0, v81, vcc
	v_add_co_u32_e32 v52, vcc, s97, v80
	v_add_u32_e32 v112, 1, v22
	s_nop 0
	v_addc_co_u32_e32 v53, vcc, 0, v81, vcc
	v_add_co_u32_e32 v56, vcc, s48, v80
	global_load_dwordx4 v[48:51], v[48:49], off
	s_nop 0
	global_load_dwordx4 v[52:55], v[52:53], off
	v_addc_co_u32_e32 v57, vcc, 0, v81, vcc
	v_add_co_u32_e32 v60, vcc, s49, v80
	v_ashrrev_i32_e32 v113, 31, v112
	s_nop 0
	v_addc_co_u32_e32 v61, vcc, 0, v81, vcc
	v_add_co_u32_e32 v64, vcc, s81, v80
	global_load_dwordx4 v[56:59], v[56:57], off
	s_nop 0
	global_load_dwordx4 v[60:63], v[60:61], off
	v_addc_co_u32_e32 v65, vcc, 0, v81, vcc
	v_add_co_u32_e32 v68, vcc, s60, v80
	v_lshlrev_b64 v[92:93], 11, v[112:113]
	s_nop 0
	v_addc_co_u32_e32 v69, vcc, 0, v81, vcc
	v_add_co_u32_e32 v72, vcc, s61, v80
	global_load_dwordx4 v[64:67], v[64:65], off
	s_nop 0
	global_load_dwordx4 v[68:71], v[68:69], off
	v_addc_co_u32_e32 v73, vcc, 0, v81, vcc
	v_add_co_u32_e32 v76, vcc, s91, v80
	v_lshl_add_u64 v[100:101], v[24:25], 0, v[92:93]
	s_nop 0
	v_addc_co_u32_e32 v77, vcc, 0, v81, vcc
	v_add_co_u32_e32 v82, vcc, s93, v80
	global_load_dwordx4 v[72:75], v[72:73], off
	s_nop 0
	global_load_dwordx4 v[76:79], v[76:77], off
	v_addc_co_u32_e32 v83, vcc, 0, v81, vcc
	v_add_co_u32_e32 v84, vcc, s33, v80
	s_movk_i32 s4, 0x7fff
	s_nop 0
	v_addc_co_u32_e32 v85, vcc, 0, v81, vcc
	global_load_dwordx4 v[80:83], v[82:83], off
	s_nop 0
	global_load_dwordx4 v[84:87], v[84:85], off
	s_waitcnt vmcnt(15)
	v_pk_add_f32 v[18:19], v[18:19], 0 op_sel_hi:[1,0]
	global_load_dwordx4 v[88:91], v[96:97], off
	global_load_dwordx4 v[92:95], v[100:101], off offset:1024
	s_nop 0
	global_load_dwordx4 v[96:99], v[96:97], off offset:1024
	v_pk_add_f32 v[20:21], v[20:21], 0 op_sel_hi:[1,0]
	global_load_dwordx4 v[100:103], v[100:101], off
	v_add_u32_e32 v122, 2, v22
	v_ashrrev_i32_e32 v123, 31, v122
	v_lshlrev_b64 v[122:123], 11, v[122:123]
	v_lshl_add_u64 v[122:123], v[24:25], 0, v[122:123]
	global_load_dwordx4 v[104:107], v[122:123], off
	global_load_dwordx4 v[108:111], v[122:123], off offset:1024
	v_add_u32_e32 v122, 3, v22
	v_ashrrev_i32_e32 v123, 31, v122
	v_lshlrev_b64 v[122:123], 11, v[122:123]
	v_lshl_add_u64 v[122:123], v[24:25], 0, v[122:123]
	global_load_dwordx4 v[114:117], v[122:123], off
	global_load_dwordx4 v[118:121], v[122:123], off offset:1024
	s_waitcnt vmcnt(22)
	v_pk_add_f32 v[18:19], v[18:19], v[28:29]
	v_pk_add_f32 v[20:21], v[20:21], v[30:31]
	v_add_u32_e32 v28, 3, v22
	v_ashrrev_i32_e32 v29, 31, v28
	s_waitcnt vmcnt(21)
	v_pk_add_f32 v[18:19], v[18:19], v[32:33]
	s_waitcnt vmcnt(20)
	v_pk_add_f32 v[18:19], v[18:19], v[36:37]
	v_pk_add_f32 v[20:21], v[20:21], v[34:35]
	s_waitcnt vmcnt(19)
	v_pk_add_f32 v[18:19], v[18:19], v[40:41]
	s_waitcnt vmcnt(18)
	v_pk_add_f32 v[18:19], v[18:19], v[44:45]
	v_pk_add_f32 v[20:21], v[20:21], v[38:39]
	s_waitcnt vmcnt(17)
	v_pk_add_f32 v[18:19], v[18:19], v[48:49]
	s_waitcnt vmcnt(16)
	v_pk_add_f32 v[18:19], v[18:19], v[52:53]
	v_pk_add_f32 v[20:21], v[20:21], v[42:43]
	v_add_u32_e32 v48, 2, v22
	v_pk_add_f32 v[20:21], v[20:21], v[46:47]
	v_ashrrev_i32_e32 v49, 31, v48
	v_pk_add_f32 v[20:21], v[20:21], v[50:51]
	s_waitcnt vmcnt(15)
	v_pk_add_f32 v[18:19], v[18:19], v[56:57]
	s_waitcnt vmcnt(14)
	v_pk_add_f32 v[18:19], v[18:19], v[60:61]
	v_pk_add_f32 v[20:21], v[20:21], v[54:55]
	s_waitcnt vmcnt(13)
	v_pk_add_f32 v[18:19], v[18:19], v[64:65]
	s_waitcnt vmcnt(12)
	v_pk_add_f32 v[18:19], v[18:19], v[68:69]
	v_pk_add_f32 v[20:21], v[20:21], v[58:59]
	s_waitcnt vmcnt(11)
	v_pk_add_f32 v[18:19], v[18:19], v[72:73]
	s_waitcnt vmcnt(10)
	v_pk_add_f32 v[18:19], v[18:19], v[76:77]
	v_pk_add_f32 v[20:21], v[20:21], v[62:63]
	s_waitcnt vmcnt(9)
	v_pk_add_f32 v[18:19], v[18:19], v[80:81]
	s_waitcnt vmcnt(8)
	v_pk_add_f32 v[18:19], v[18:19], v[84:85]
	v_pk_add_f32 v[20:21], v[20:21], v[66:67]
	v_pk_fma_f32 v[18:19], v[18:19], s[90:91], v[210:211] op_sel_hi:[1,0,0]
	v_pk_add_f32 v[20:21], v[20:21], v[70:71]
	v_mul_f32_e32 v0, 0x4b800000, v18
	v_cmp_gt_f32_e32 vcc, s10, v18
	v_cmp_gt_f32_e64 s[40:41], s10, v19
	v_pk_add_f32 v[20:21], v[20:21], v[74:75]
	v_cndmask_b32_e32 v0, v18, v0, vcc
	v_mul_f32_e32 v18, 0x4b800000, v19
	v_rsq_f32_e32 v0, v0
	v_cndmask_b32_e64 v18, v19, v18, s[40:41]
	v_rsq_f32_e32 v18, v18
	v_pk_add_f32 v[20:21], v[20:21], v[78:79]
	v_mul_f32_e32 v19, 0x45800000, v0
	v_cndmask_b32_e32 v40, v0, v19, vcc
	v_mul_f32_e32 v0, 0x45800000, v18
	v_cndmask_b32_e64 v44, v18, v0, s[40:41]
	v_lshlrev_b64 v[18:19], 11, v[48:49]
	v_lshl_add_u64 v[18:19], v[24:25], 0, v[18:19]
	v_pk_add_f32 v[20:21], v[20:21], v[82:83]
	v_lshlrev_b64 v[18:19], 11, v[28:29]
	v_pk_add_f32 v[20:21], v[20:21], v[86:87]
	v_lshl_add_u64 v[18:19], v[24:25], 0, v[18:19]
	v_pk_fma_f32 v[20:21], v[20:21], s[90:91], v[210:211] op_sel_hi:[1,0,0]
	s_waitcnt vmcnt(7)
	v_lshlrev_b32_e32 v36, 16, v89
	v_mul_f32_e32 v0, 0x4b800000, v20
	v_cmp_gt_f32_e32 vcc, s10, v20
	v_cmp_gt_f32_e64 s[40:41], s10, v21
	v_and_b32_e32 v37, 0xffff0000, v89
	v_cndmask_b32_e32 v0, v20, v0, vcc
	v_mul_f32_e32 v20, 0x4b800000, v21
	v_cndmask_b32_e64 v20, v21, v20, s[40:41]
	v_rsq_f32_e32 v34, v20
	v_rsq_f32_e32 v0, v0
	v_pk_mul_f32 v[36:37], v[40:41], v[36:37] op_sel_hi:[0,1]
	v_lshlrev_b32_e32 v46, 16, v90
	v_and_b32_e32 v47, 0xffff0000, v90
	v_mul_f32_e32 v35, 0x45800000, v0
	v_cndmask_b32_e32 v38, v0, v35, vcc
	v_mul_f32_e32 v0, 0x45800000, v34
	v_cndmask_b32_e64 v0, v34, v0, s[40:41]
	v_lshlrev_b64 v[34:35], 12, v[22:23]
	v_lshl_add_u64 v[42:43], v[26:27], 0, v[34:35]
	v_lshlrev_b32_e32 v34, 16, v88
	v_and_b32_e32 v35, 0xffff0000, v88
	v_pk_mul_f32 v[34:35], v[40:41], v[34:35] op_sel_hi:[0,1]
	v_lshlrev_b32_e32 v50, 16, v91
	v_and_b32_e32 v51, 0xffff0000, v91
	v_pk_mul_f32 v[36:37], v[8:9], v[36:37]
	v_pk_mul_f32 v[34:35], v[6:7], v[34:35]
	global_store_dwordx4 v[42:43], v[34:37], off
	v_lshlrev_b64 v[28:29], 12, v[28:29]
	v_add_u32_e32 v22, s22, v22
	v_pk_mul_f32 v[34:35], v[40:41], v[46:47] op_sel_hi:[0,1]
	v_pk_mul_f32 v[36:37], v[40:41], v[50:51] op_sel_hi:[0,1]
	v_pk_mul_f32 v[36:37], v[4:5], v[36:37]
	v_pk_mul_f32 v[34:35], v[2:3], v[34:35]
	global_store_dwordx4 v[42:43], v[34:37], off offset:16
	s_waitcnt vmcnt(7)
	v_lshlrev_b32_e32 v46, 16, v98
	v_and_b32_e32 v47, 0xffff0000, v98
	v_lshlrev_b32_e32 v34, 16, v96
	v_and_b32_e32 v35, 0xffff0000, v96
	v_lshlrev_b32_e32 v36, 16, v97
	v_and_b32_e32 v37, 0xffff0000, v97
	v_pk_mul_f32 v[34:35], v[40:41], v[34:35] op_sel_hi:[0,1]
	v_pk_mul_f32 v[36:37], v[40:41], v[36:37] op_sel_hi:[0,1]
	v_lshlrev_b32_e32 v50, 16, v99
	v_and_b32_e32 v51, 0xffff0000, v99
	v_pk_mul_f32 v[36:37], v[16:17], v[36:37]
	v_pk_mul_f32 v[34:35], v[14:15], v[34:35]
	global_store_dwordx4 v[42:43], v[34:37], off offset:2048
	v_cmp_lt_i32_e32 vcc, s4, v22
	s_or_b64 s[20:21], vcc, s[20:21]
	v_pk_mul_f32 v[34:35], v[40:41], v[46:47] op_sel_hi:[0,1]
	v_pk_mul_f32 v[36:37], v[40:41], v[50:51] op_sel_hi:[0,1]
	v_pk_mul_f32 v[36:37], v[12:13], v[36:37]
	v_pk_mul_f32 v[34:35], v[10:11], v[34:35]
	global_store_dwordx4 v[42:43], v[34:37], off offset:2064
	s_waitcnt vmcnt(8)
	v_lshlrev_b32_e32 v42, 16, v102
	v_and_b32_e32 v43, 0xffff0000, v102
	v_lshlrev_b64 v[34:35], 12, v[112:113]
	v_lshl_add_u64 v[40:41], v[26:27], 0, v[34:35]
	v_lshlrev_b32_e32 v34, 16, v100
	v_and_b32_e32 v35, 0xffff0000, v100
	v_lshlrev_b32_e32 v36, 16, v101
	v_and_b32_e32 v37, 0xffff0000, v101
	v_pk_mul_f32 v[34:35], v[44:45], v[34:35] op_sel_hi:[0,1]
	v_pk_mul_f32 v[36:37], v[44:45], v[36:37] op_sel_hi:[0,1]
	v_lshlrev_b32_e32 v46, 16, v103
	v_and_b32_e32 v47, 0xffff0000, v103
	v_pk_mul_f32 v[36:37], v[8:9], v[36:37]
	v_pk_mul_f32 v[34:35], v[6:7], v[34:35]
	global_store_dwordx4 v[40:41], v[34:37], off
	s_nop 1
	v_pk_mul_f32 v[34:35], v[44:45], v[42:43] op_sel_hi:[0,1]
	v_pk_mul_f32 v[36:37], v[44:45], v[46:47] op_sel_hi:[0,1]
	v_pk_mul_f32 v[36:37], v[4:5], v[36:37]
	v_pk_mul_f32 v[34:35], v[2:3], v[34:35]
	global_store_dwordx4 v[40:41], v[34:37], off offset:16
	v_lshlrev_b32_e32 v42, 16, v94
	v_and_b32_e32 v43, 0xffff0000, v94
	v_lshlrev_b32_e32 v34, 16, v92
	v_and_b32_e32 v35, 0xffff0000, v92
	v_lshlrev_b32_e32 v36, 16, v93
	v_and_b32_e32 v37, 0xffff0000, v93
	v_pk_mul_f32 v[34:35], v[44:45], v[34:35] op_sel_hi:[0,1]
	v_pk_mul_f32 v[36:37], v[44:45], v[36:37] op_sel_hi:[0,1]
	v_lshlrev_b32_e32 v46, 16, v95
	v_and_b32_e32 v47, 0xffff0000, v95
	v_pk_mul_f32 v[36:37], v[16:17], v[36:37]
	v_pk_mul_f32 v[34:35], v[14:15], v[34:35]
	global_store_dwordx4 v[40:41], v[34:37], off offset:2048
	s_nop 1
	v_pk_mul_f32 v[34:35], v[44:45], v[42:43] op_sel_hi:[0,1]
	v_pk_mul_f32 v[36:37], v[44:45], v[46:47] op_sel_hi:[0,1]
	v_pk_mul_f32 v[36:37], v[12:13], v[36:37]
	v_pk_mul_f32 v[34:35], v[10:11], v[34:35]
	global_store_dwordx4 v[40:41], v[34:37], off offset:2064
	s_waitcnt vmcnt(11)
	v_lshlrev_b32_e32 v42, 16, v106
	v_and_b32_e32 v43, 0xffff0000, v106
	v_lshlrev_b64 v[34:35], 12, v[48:49]
	v_lshl_add_u64 v[40:41], v[26:27], 0, v[34:35]
	v_lshlrev_b32_e32 v34, 16, v104
	v_and_b32_e32 v35, 0xffff0000, v104
	v_lshlrev_b32_e32 v36, 16, v105
	v_and_b32_e32 v37, 0xffff0000, v105
	v_pk_mul_f32 v[34:35], v[38:39], v[34:35] op_sel_hi:[0,1]
	v_pk_mul_f32 v[36:37], v[38:39], v[36:37] op_sel_hi:[0,1]
	v_lshlrev_b32_e32 v44, 16, v107
	v_and_b32_e32 v45, 0xffff0000, v107
	v_pk_mul_f32 v[36:37], v[8:9], v[36:37]
	v_pk_mul_f32 v[34:35], v[6:7], v[34:35]
	global_store_dwordx4 v[40:41], v[34:37], off
	s_nop 1
	v_pk_mul_f32 v[34:35], v[38:39], v[42:43] op_sel_hi:[0,1]
	v_pk_mul_f32 v[36:37], v[38:39], v[44:45] op_sel_hi:[0,1]
	v_pk_mul_f32 v[36:37], v[4:5], v[36:37]
	v_pk_mul_f32 v[34:35], v[2:3], v[34:35]
	global_store_dwordx4 v[40:41], v[34:37], off offset:16
	s_waitcnt vmcnt(12)
	v_lshlrev_b32_e32 v42, 16, v110
	v_and_b32_e32 v43, 0xffff0000, v110
	v_lshlrev_b32_e32 v34, 16, v108
	v_and_b32_e32 v35, 0xffff0000, v108
	v_lshlrev_b32_e32 v36, 16, v109
	v_and_b32_e32 v37, 0xffff0000, v109
	v_pk_mul_f32 v[34:35], v[38:39], v[34:35] op_sel_hi:[0,1]
	v_pk_mul_f32 v[36:37], v[38:39], v[36:37] op_sel_hi:[0,1]
	v_lshlrev_b32_e32 v44, 16, v111
	v_and_b32_e32 v45, 0xffff0000, v111
	v_pk_mul_f32 v[36:37], v[16:17], v[36:37]
	v_pk_mul_f32 v[34:35], v[14:15], v[34:35]
	global_store_dwordx4 v[40:41], v[34:37], off offset:2048
	s_nop 1
	v_pk_mul_f32 v[34:35], v[38:39], v[42:43] op_sel_hi:[0,1]
	v_pk_mul_f32 v[36:37], v[38:39], v[44:45] op_sel_hi:[0,1]
	v_pk_mul_f32 v[36:37], v[12:13], v[36:37]
	v_pk_mul_f32 v[34:35], v[10:11], v[34:35]
	global_store_dwordx4 v[40:41], v[34:37], off offset:2064
	s_nop 1
	v_lshl_add_u64 v[34:35], v[26:27], 0, v[28:29]
	s_waitcnt vmcnt(13)
	v_mov_b64_e32 v[30:31], v[114:115]
	v_mov_b64_e32 v[32:33], v[116:117]
	v_lshlrev_b32_e32 v28, 16, v30
	v_and_b32_e32 v29, 0xffff0000, v30
	v_lshlrev_b32_e32 v30, 16, v31
	v_and_b32_e32 v31, 0xffff0000, v31
	v_pk_mul_f32 v[28:29], v[0:1], v[28:29] op_sel_hi:[0,1]
	v_pk_mul_f32 v[30:31], v[0:1], v[30:31] op_sel_hi:[0,1]
	v_lshlrev_b32_e32 v36, 16, v32
	v_and_b32_e32 v37, 0xffff0000, v32
	v_lshlrev_b32_e32 v32, 16, v33
	v_and_b32_e32 v33, 0xffff0000, v33
	v_pk_mul_f32 v[30:31], v[8:9], v[30:31]
	v_pk_mul_f32 v[28:29], v[6:7], v[28:29]
	global_store_dwordx4 v[34:35], v[28:31], off
	s_nop 1
	v_pk_mul_f32 v[28:29], v[0:1], v[36:37] op_sel_hi:[0,1]
	v_pk_mul_f32 v[30:31], v[0:1], v[32:33] op_sel_hi:[0,1]
	v_pk_mul_f32 v[30:31], v[4:5], v[30:31]
	v_pk_mul_f32 v[28:29], v[2:3], v[28:29]
	global_store_dwordx4 v[34:35], v[28:31], off offset:16
	s_waitcnt vmcnt(14)
	v_mov_b64_e32 v[18:19], v[118:119]
	v_mov_b64_e32 v[20:21], v[120:121]
	v_lshlrev_b32_e32 v32, 16, v21
	v_and_b32_e32 v33, 0xffff0000, v21
	v_lshlrev_b32_e32 v28, 16, v18
	v_and_b32_e32 v29, 0xffff0000, v18
	v_lshlrev_b32_e32 v18, 16, v19
	v_and_b32_e32 v19, 0xffff0000, v19
	v_pk_mul_f32 v[28:29], v[0:1], v[28:29] op_sel_hi:[0,1]
	v_pk_mul_f32 v[18:19], v[0:1], v[18:19] op_sel_hi:[0,1]
	v_lshlrev_b32_e32 v30, 16, v20
	v_and_b32_e32 v31, 0xffff0000, v20
	v_pk_mul_f32 v[20:21], v[16:17], v[18:19]
	v_pk_mul_f32 v[18:19], v[14:15], v[28:29]
	global_store_dwordx4 v[34:35], v[18:21], off offset:2048
	s_nop 1
	v_pk_mul_f32 v[18:19], v[0:1], v[30:31] op_sel_hi:[0,1]
	v_pk_mul_f32 v[20:21], v[0:1], v[32:33] op_sel_hi:[0,1]
	v_pk_mul_f32 v[20:21], v[12:13], v[20:21]
	v_pk_mul_f32 v[18:19], v[10:11], v[18:19]
	global_store_dwordx4 v[34:35], v[18:21], off offset:2064
	s_andn2_b64 exec, exec, s[20:21]
	s_cbranch_execnz .LBB0_15
